# SGU load hoist + 16-byte attention epilogue stores, padded so the later GEMM loops keep the byte placement they have in v38
# speedup vs baseline: 1.0070x; 1.0037x over previous
; DI unsigned pk2(float lo, float hi) { typedef float v2f __attribute__((ext_vector_type(2))); typedef __bf16 v2b __attribute__((ext_vector_type(2))); v2f v = {lo, hi}; v2b b = __builtin_convertvector(v, v2b); return __builtin_bit_cast(unsigned, b); }
; DI float xhalf_sum(float m) { auto rr = __builtin_amdgcn_permlane32_swap(__float_as_uint(m), __float_as_uint(m), false, false); return __uint_as_float(rr[0]) + __uint_as_float(rr[1]); }
; template <int DQK, int DV, bool CAUSAL, int KT, bool PRIO>
; DI void attn_unit(const bf16_t* Qb, int qpitch, const bf16_t* Kb, int kpitch, const bf16_t* Vtb, int vpitch, bf16_t* Ob, int opitch, int q0, int nt, LAS unsigned char* lds, float kbound, const float* qgain, const int* qpos, float qscale) {
;     ...
;     lrun = xhalf_sum(lrun);
;     const float inv = 1.0f / lrun;
;     bf16_t* orow = Ob + (size_t)(32 * w + r) * opitch;
; #pragma unroll
;     for (int d = 0; d < DV / 32; ++d)
; #pragma unroll
;         for (int g = 0; g < 4; ++g) { u32x2 wv; wv.x = pk2(o[d][4 * g] * inv, o[d][4 * g + 1] * inv); wv.y = pk2(o[d][4 * g + 2] * inv, o[d][4 * g + 3] * inv);
;             *(u32x2*)(orow + 32 * d + 8 * g + 4 * h) = wv; }
.LBB0_1479:
	v_mov_b32_e32 v2, v0
	s_nop 1
	v_permlane32_swap_b32_e32 v0, v2
	v_add_f32_e32 v0, v0, v2
	v_div_scale_f32 v2, s[2:3], v0, v0, 1.0
	v_rcp_f32_e32 v3, v2
	s_lshl_b64 s[2:3], s[26:27], 10
	s_add_u32 s2, s65, s2
	s_addc_u32 s3, s66, s3
	v_fma_f32 v4, -v2, v3, 1.0
	v_fmac_f32_e32 v3, v4, v3
	v_div_scale_f32 v4, vcc, 1.0, v0, 1.0
	v_mul_f32_e32 v5, v4, v3
	v_fma_f32 v6, -v2, v5, v4
	v_fmac_f32_e32 v5, v6, v3
	v_fma_f32 v2, -v2, v5, v4
	v_div_fmas_f32 v2, v2, v3, v5
	v_div_fixup_f32 v2, v2, v0, 1.0
	v_lshlrev_b64 v[4:5], 10, v[162:163]
	v_lshl_add_u64 v[4:5], s[2:3], 0, v[4:5]
	v_lshlrev_b32_e32 v0, 2, v180
	v_lshl_add_u64 v[4:5], v[4:5], 0, v[0:1]
	v_pk_mul_f32 v[6:7], v[32:33], v[2:3] op_sel_hi:[1,0]
	v_pk_mul_f32 v[8:9], v[34:35], v[2:3] op_sel_hi:[1,0]
	v_cvt_pk_bf16_f32 v6, v6, v7
	v_cvt_pk_bf16_f32 v7, v8, v9
	v_pk_mul_f32 v[8:9], v[36:37], v[2:3] op_sel_hi:[1,0]
	v_pk_mul_f32 v[10:11], v[38:39], v[2:3] op_sel_hi:[1,0]
	v_cvt_pk_bf16_f32 v8, v8, v9
	v_cvt_pk_bf16_f32 v9, v10, v11
	s_nop 1
	v_permlane32_swap_b32_e32 v6, v8
	v_permlane32_swap_b32_e32 v7, v9
	flat_store_dwordx4 v[4:5], v[6:9]
	v_pk_mul_f32 v[10:11], v[40:41], v[2:3] op_sel_hi:[1,0]
	v_pk_mul_f32 v[12:13], v[42:43], v[2:3] op_sel_hi:[1,0]
	v_cvt_pk_bf16_f32 v10, v10, v11
	v_cvt_pk_bf16_f32 v11, v12, v13
	v_pk_mul_f32 v[12:13], v[44:45], v[2:3] op_sel_hi:[1,0]
	v_pk_mul_f32 v[14:15], v[46:47], v[2:3] op_sel_hi:[1,0]
	v_cvt_pk_bf16_f32 v12, v12, v13
	v_cvt_pk_bf16_f32 v13, v14, v15
	s_nop 1
	v_permlane32_swap_b32_e32 v10, v12
	v_permlane32_swap_b32_e32 v11, v13
	flat_store_dwordx4 v[4:5], v[10:13] offset:32
	v_pk_mul_f32 v[6:7], v[16:17], v[2:3] op_sel_hi:[1,0]
	v_pk_mul_f32 v[8:9], v[18:19], v[2:3] op_sel_hi:[1,0]
	v_cvt_pk_bf16_f32 v6, v6, v7
	v_cvt_pk_bf16_f32 v7, v8, v9
	v_pk_mul_f32 v[8:9], v[20:21], v[2:3] op_sel_hi:[1,0]
	v_pk_mul_f32 v[14:15], v[22:23], v[2:3] op_sel_hi:[1,0]
	v_cvt_pk_bf16_f32 v8, v8, v9
	v_cvt_pk_bf16_f32 v9, v14, v15
	s_nop 1
	v_permlane32_swap_b32_e32 v6, v8
	v_permlane32_swap_b32_e32 v7, v9
	flat_store_dwordx4 v[4:5], v[6:9] offset:64
	v_pk_mul_f32 v[10:11], v[24:25], v[2:3] op_sel_hi:[1,0]
	v_pk_mul_f32 v[12:13], v[26:27], v[2:3] op_sel_hi:[1,0]
	v_cvt_pk_bf16_f32 v10, v10, v11
	v_cvt_pk_bf16_f32 v11, v12, v13
	v_pk_mul_f32 v[12:13], v[28:29], v[2:3] op_sel_hi:[1,0]
	v_pk_mul_f32 v[14:15], v[30:31], v[2:3] op_sel_hi:[1,0]
	v_cvt_pk_bf16_f32 v12, v12, v13
	v_cvt_pk_bf16_f32 v13, v14, v15
	s_nop 1
	v_permlane32_swap_b32_e32 v10, v12
	v_permlane32_swap_b32_e32 v11, v13
	s_mov_b64 s[2:3], 0
	s_and_b64 vcc, exec, s[34:35]
	flat_store_dwordx4 v[4:5], v[10:13] offset:96
	s_nop 0
	s_nop 0
	s_nop 0
	s_nop 0
	s_cbranch_vccnz .LBB0_1477
